# strategy 7: DPP adds instead of ds_bpermute round trips in the postscan group-norm reductions
# baseline (speedup 1.0000x reference)
.LBB0_134:
	s_or_b64 exec, exec, s[8:9]
	s_waitcnt vmcnt(2)
	v_cvt_f32_f16_sdwa v195, v140 dst_sel:DWORD dst_unused:UNUSED_PAD src0_sel:WORD_1
	v_cvt_f32_f16_e32 v194, v140
	v_cvt_f32_f16_sdwa v213, v136 dst_sel:DWORD dst_unused:UNUSED_PAD src0_sel:WORD_1
	v_cvt_f32_f16_e32 v212, v136
	s_waitcnt vmcnt(1)
	v_cvt_f32_f16_sdwa v215, v144 dst_sel:DWORD dst_unused:UNUSED_PAD src0_sel:WORD_1
	s_waitcnt lgkmcnt(14)
	v_pk_mul_f32 v[194:195], v[16:17], v[194:195]
	v_cvt_f32_f16_e32 v214, v144
	v_pk_fma_f32 v[194:195], v[24:25], v[212:213], v[194:195]
	v_cvt_f32_f16_sdwa v213, v132 dst_sel:DWORD dst_unused:UNUSED_PAD src0_sel:WORD_1
	v_cvt_f32_f16_e32 v212, v132
	s_mov_b64 s[6:7], 0x8198100
	v_lshl_add_u64 v[192:193], v[192:193], 0, s[6:7]
	s_mov_b32 s6, 0x41800000
	v_pk_fma_f32 v[194:195], v[28:29], v[212:213], v[194:195]
	v_cvt_f32_f16_sdwa v213, v152 dst_sel:DWORD dst_unused:UNUSED_PAD src0_sel:WORD_1
	v_cvt_f32_f16_e32 v212, v152
	v_add_u32_e32 v211, 4, v211
	v_pk_mul_f32 v[212:213], v[32:33], v[212:213]
	s_nop 0
	v_pk_fma_f32 v[212:213], v[36:37], v[214:215], v[212:213]
	v_cvt_f32_f16_sdwa v215, v148 dst_sel:DWORD dst_unused:UNUSED_PAD src0_sel:WORD_1
	v_cvt_f32_f16_e32 v214, v148
	v_pk_fma_f32 v[212:213], v[40:41], v[214:215], v[212:213]
	s_nop 0
	v_pk_mul_f32 v[194:195], v[194:195], v[212:213]
	s_nop 0
	v_pk_mul_f32 v[194:195], v[44:45], v[194:195]
	s_nop 0
	v_add_f32_e32 v132, 0, v194
	v_add_f32_e32 v144, v195, v132
	v_cvt_f32_f16_sdwa v195, v141 dst_sel:DWORD dst_unused:UNUSED_PAD src0_sel:WORD_1
	v_cvt_f32_f16_e32 v194, v141
	v_pk_mul_f32 v[140:141], v[18:19], v[194:195]
	v_cvt_f32_f16_sdwa v195, v137 dst_sel:DWORD dst_unused:UNUSED_PAD src0_sel:WORD_1
	v_cvt_f32_f16_e32 v194, v137
	v_pk_fma_f32 v[136:137], v[26:27], v[194:195], v[140:141]
	v_cvt_f32_f16_sdwa v141, v133 dst_sel:DWORD dst_unused:UNUSED_PAD src0_sel:WORD_1
	v_cvt_f32_f16_e32 v140, v133
	v_pk_fma_f32 v[132:133], v[30:31], v[140:141], v[136:137]
	v_cvt_f32_f16_sdwa v137, v153 dst_sel:DWORD dst_unused:UNUSED_PAD src0_sel:WORD_1
	v_cvt_f32_f16_e32 v136, v153
	v_cvt_f32_f16_sdwa v141, v145 dst_sel:DWORD dst_unused:UNUSED_PAD src0_sel:WORD_1
	v_cvt_f32_f16_e32 v140, v145
	v_cvt_f32_f16_sdwa v145, v117 dst_sel:DWORD dst_unused:UNUSED_PAD src0_sel:WORD_1
	v_pk_mul_f32 v[136:137], v[34:35], v[136:137]
	s_nop 0
	v_pk_fma_f32 v[136:137], v[38:39], v[140:141], v[136:137]
	v_cvt_f32_f16_sdwa v141, v149 dst_sel:DWORD dst_unused:UNUSED_PAD src0_sel:WORD_1
	v_cvt_f32_f16_e32 v140, v149
	v_pk_fma_f32 v[136:137], v[42:43], v[140:141], v[136:137]
	s_nop 0
	v_pk_mul_f32 v[132:133], v[132:133], v[136:137]
	v_cvt_f32_f16_sdwa v137, v138 dst_sel:DWORD dst_unused:UNUSED_PAD src0_sel:WORD_1
	v_pk_mul_f32 v[132:133], v[46:47], v[132:133]
	v_cvt_f32_f16_e32 v136, v138
	v_add_f32_e32 v132, v132, v144
	v_add_f32_e32 v144, v133, v132
	v_cvt_f32_f16_sdwa v133, v142 dst_sel:DWORD dst_unused:UNUSED_PAD src0_sel:WORD_1
	v_cvt_f32_f16_e32 v132, v142
	v_cvt_f32_f16_sdwa v141, v146 dst_sel:DWORD dst_unused:UNUSED_PAD src0_sel:WORD_1
	v_cvt_f32_f16_e32 v140, v146
	v_pk_mul_f32 v[132:133], v[20:21], v[132:133]
	s_nop 0
	v_pk_fma_f32 v[132:133], v[48:49], v[136:137], v[132:133]
	v_cvt_f32_f16_sdwa v137, v134 dst_sel:DWORD dst_unused:UNUSED_PAD src0_sel:WORD_1
	v_cvt_f32_f16_e32 v136, v134
	v_cvt_f32_f16_e32 v134, v155
	v_pk_fma_f32 v[132:133], v[52:53], v[136:137], v[132:133]
	v_cvt_f32_f16_sdwa v137, v154 dst_sel:DWORD dst_unused:UNUSED_PAD src0_sel:WORD_1
	v_cvt_f32_f16_e32 v136, v154
	s_waitcnt lgkmcnt(13)
	v_pk_mul_f32 v[136:137], v[56:57], v[136:137]
	s_waitcnt lgkmcnt(12)
	v_pk_fma_f32 v[136:137], v[60:61], v[140:141], v[136:137]
	v_cvt_f32_f16_sdwa v141, v150 dst_sel:DWORD dst_unused:UNUSED_PAD src0_sel:WORD_1
	v_cvt_f32_f16_e32 v140, v150
	s_waitcnt lgkmcnt(11)
	v_pk_fma_f32 v[136:137], v[64:65], v[140:141], v[136:137]
	s_nop 0
	v_pk_mul_f32 v[132:133], v[132:133], v[136:137]
	v_cvt_f32_f16_sdwa v137, v139 dst_sel:DWORD dst_unused:UNUSED_PAD src0_sel:WORD_1
	s_waitcnt lgkmcnt(10)
	v_pk_mul_f32 v[132:133], v[68:69], v[132:133]
	v_cvt_f32_f16_e32 v136, v139
	v_add_f32_e32 v132, v132, v144
	v_add_f32_e32 v138, v133, v132
	v_cvt_f32_f16_sdwa v133, v143 dst_sel:DWORD dst_unused:UNUSED_PAD src0_sel:WORD_1
	v_cvt_f32_f16_e32 v132, v143
	v_cvt_f32_f16_sdwa v139, v116 dst_sel:DWORD dst_unused:UNUSED_PAD src0_sel:WORD_1
	v_cvt_f32_f16_sdwa v141, v112 dst_sel:DWORD dst_unused:UNUSED_PAD src0_sel:WORD_1
	v_cvt_f32_f16_e32 v140, v112
	v_pk_mul_f32 v[132:133], v[22:23], v[132:133]
	v_cvt_f32_f16_e32 v144, v117
	v_pk_fma_f32 v[132:133], v[50:51], v[136:137], v[132:133]
	v_cvt_f32_f16_sdwa v137, v135 dst_sel:DWORD dst_unused:UNUSED_PAD src0_sel:WORD_1
	v_cvt_f32_f16_e32 v136, v135
	v_cvt_f32_f16_sdwa v135, v155 dst_sel:DWORD dst_unused:UNUSED_PAD src0_sel:WORD_1
	v_cvt_f32_f16_sdwa v117, v113 dst_sel:DWORD dst_unused:UNUSED_PAD src0_sel:WORD_1
	v_pk_fma_f32 v[132:133], v[54:55], v[136:137], v[132:133]
	v_cvt_f32_f16_sdwa v137, v147 dst_sel:DWORD dst_unused:UNUSED_PAD src0_sel:WORD_1
	v_cvt_f32_f16_e32 v136, v147
	v_pk_mul_f32 v[134:135], v[58:59], v[134:135]
	s_nop 0
	v_pk_fma_f32 v[134:135], v[62:63], v[136:137], v[134:135]
	v_cvt_f32_f16_sdwa v137, v151 dst_sel:DWORD dst_unused:UNUSED_PAD src0_sel:WORD_1
	v_cvt_f32_f16_e32 v136, v151
	v_pk_fma_f32 v[134:135], v[66:67], v[136:137], v[134:135]
	s_nop 0
	v_pk_mul_f32 v[132:133], v[132:133], v[134:135]
	s_nop 0
	v_pk_mul_f32 v[132:133], v[70:71], v[132:133]
	s_nop 0
	v_add_f32_e32 v132, v132, v138
	v_add_f32_e32 v132, v133, v132
	v_cvt_f32_f16_e32 v138, v116
	v_cvt_f32_f16_e32 v116, v113
	s_waitcnt vmcnt(0)
	v_cvt_f32_f16_sdwa v113, v129 dst_sel:DWORD dst_unused:UNUSED_PAD src0_sel:WORD_1
	s_waitcnt lgkmcnt(0)
	s_nop 1
	v_add_f32_dpp v132, v132, v132 quad_perm:[1,0,3,2] row_mask:0xf bank_mask:0xf
	v_pk_add_f32 v[142:143], v[138:139], v[140:141]
	v_cvt_f32_f16_sdwa v141, v120 dst_sel:DWORD dst_unused:UNUSED_PAD src0_sel:WORD_1
	v_pk_mul_f32 v[138:139], v[142:143], s[6:7] op_sel_hi:[1,0]
	v_cvt_f32_f16_e32 v140, v120
	s_waitcnt lgkmcnt(0)
	s_nop 1
	v_add_f32_dpp v132, v132, v132 quad_perm:[2,3,0,1] row_mask:0xf bank_mask:0xf
	v_add_f32_e32 v112, 0, v138
	v_add_f32_e32 v137, v139, v112
	v_cvt_f32_f16_e32 v112, v129
	v_cvt_f32_f16_sdwa v139, v128 dst_sel:DWORD dst_unused:UNUSED_PAD src0_sel:WORD_1
	v_cvt_f32_f16_e32 v138, v128
	v_cvt_f32_f16_sdwa v129, v121 dst_sel:DWORD dst_unused:UNUSED_PAD src0_sel:WORD_1
	v_cvt_f32_f16_e32 v128, v121
	v_cvt_f32_f16_sdwa v121, v125 dst_sel:DWORD dst_unused:UNUSED_PAD src0_sel:WORD_1
	v_cvt_f32_f16_e32 v120, v125
	v_pk_mul_f32 v[112:113], v[74:75], v[112:113]
	s_waitcnt lgkmcnt(0)
	s_nop 1
	v_add_f32_dpp v136, v132, v132 row_half_mirror row_mask:0xf bank_mask:0xf
	v_add_u32_e32 v132, s1, v206
	v_pk_mul_f32 v[138:139], v[72:73], v[138:139]
	v_pk_fma_f32 v[112:113], v[78:79], v[128:129], v[112:113]
	ds_read_b128 v[132:135], v132
	v_pk_fma_f32 v[138:139], v[76:77], v[140:141], v[138:139]
	v_cvt_f32_f16_sdwa v141, v124 dst_sel:DWORD dst_unused:UNUSED_PAD src0_sel:WORD_1
	v_cvt_f32_f16_e32 v140, v124
	v_pk_fma_f32 v[112:113], v[82:83], v[120:121], v[112:113]
	v_cvt_f32_f16_sdwa v121, v118 dst_sel:DWORD dst_unused:UNUSED_PAD src0_sel:WORD_1
	v_cvt_f32_f16_e32 v120, v118
	v_cvt_f32_f16_sdwa v125, v114 dst_sel:DWORD dst_unused:UNUSED_PAD src0_sel:WORD_1
	v_cvt_f32_f16_e32 v124, v114
	v_pk_add_f32 v[144:145], v[144:145], v[116:117]
	v_pk_fma_f32 v[138:139], v[80:81], v[140:141], v[138:139]
	v_pk_mul_f32 v[116:117], v[144:145], s[6:7] op_sel_hi:[1,0]
	v_pk_add_f32 v[128:129], v[120:121], v[124:125]
	v_add_f32_e32 v116, v116, v137
	v_cvt_f32_f16_sdwa v121, v130 dst_sel:DWORD dst_unused:UNUSED_PAD src0_sel:WORD_1
	v_cvt_f32_f16_e32 v120, v130
	s_waitcnt lgkmcnt(0)
	v_cvt_f32_f16_e32 v140, v132
	v_cvt_f32_f16_sdwa v141, v132 dst_sel:DWORD dst_unused:UNUSED_PAD src0_sel:WORD_1
	v_add_f32_e32 v137, v117, v116
	v_cvt_f32_f16_e32 v116, v133
	v_cvt_f32_f16_sdwa v117, v133 dst_sel:DWORD dst_unused:UNUSED_PAD src0_sel:WORD_1
	v_cvt_f32_f16_sdwa v133, v122 dst_sel:DWORD dst_unused:UNUSED_PAD src0_sel:WORD_1
	v_cvt_f32_f16_e32 v132, v122
	v_pk_mul_f32 v[120:121], v[96:97], v[120:121]
	v_cvt_f32_f16_e32 v118, v115
	v_pk_mul_f32 v[124:125], v[128:129], s[6:7] op_sel_hi:[1,0]
	v_pk_fma_f32 v[120:121], v[100:101], v[132:133], v[120:121]
	v_cvt_f32_f16_sdwa v133, v126 dst_sel:DWORD dst_unused:UNUSED_PAD src0_sel:WORD_1
	v_cvt_f32_f16_e32 v132, v126
	v_add_f32_e32 v114, v124, v137
	v_add_f32_e32 v126, v125, v114
	v_cvt_f32_f16_e32 v124, v134
	v_pk_fma_f32 v[120:121], v[104:105], v[132:133], v[120:121]
	v_cvt_f32_f16_sdwa v133, v119 dst_sel:DWORD dst_unused:UNUSED_PAD src0_sel:WORD_1
	v_cvt_f32_f16_e32 v132, v119
	v_cvt_f32_f16_sdwa v119, v115 dst_sel:DWORD dst_unused:UNUSED_PAD src0_sel:WORD_1
	v_cvt_f32_f16_sdwa v125, v134 dst_sel:DWORD dst_unused:UNUSED_PAD src0_sel:WORD_1
	s_addk_i32 s1, 0x2000
	s_cmp_lg_u32 s1, 0x10000
	v_pk_add_f32 v[114:115], v[132:133], v[118:119]
	v_cvt_f32_f16_sdwa v133, v131 dst_sel:DWORD dst_unused:UNUSED_PAD src0_sel:WORD_1
	v_pk_mul_f32 v[118:119], v[114:115], s[6:7] op_sel_hi:[1,0]
	v_cvt_f32_f16_e32 v132, v131
	v_add_f32_e32 v118, v118, v126
	v_add_f32_e32 v118, v119, v118
	v_pk_mul_f32 v[130:131], v[98:99], v[132:133]
	v_cvt_f32_f16_sdwa v133, v123 dst_sel:DWORD dst_unused:UNUSED_PAD src0_sel:WORD_1
	v_cvt_f32_f16_e32 v132, v123
	s_waitcnt lgkmcnt(0)
	s_nop 1
	v_add_f32_dpp v118, v118, v118 quad_perm:[1,0,3,2] row_mask:0xf bank_mask:0xf
	v_pk_fma_f32 v[122:123], v[102:103], v[132:133], v[130:131]
	v_cvt_f32_f16_sdwa v131, v127 dst_sel:DWORD dst_unused:UNUSED_PAD src0_sel:WORD_1
	v_cvt_f32_f16_e32 v130, v127
	s_waitcnt lgkmcnt(0)
	s_nop 1
	v_add_f32_dpp v118, v118, v118 quad_perm:[2,3,0,1] row_mask:0xf bank_mask:0xf
	v_pk_fma_f32 v[122:123], v[106:107], v[130:131], v[122:123]
	s_waitcnt lgkmcnt(0)
	s_nop 1
	v_add_f32_dpp v118, v118, v118 row_half_mirror row_mask:0xf bank_mask:0xf
	v_mul_f32_e32 v118, 0x3c800000, v118
	v_pk_fma_f32 v[126:127], v[142:143], s[6:7], v[118:119] op_sel_hi:[1,0,0] neg_lo:[0,0,1] neg_hi:[0,0,1]
	v_pk_fma_f32 v[132:133], v[144:145], s[6:7], v[118:119] op_sel_hi:[1,0,0] neg_lo:[0,0,1] neg_hi:[0,0,1]
	v_pk_mul_f32 v[130:131], v[126:127], v[126:127]
	v_pk_mul_f32 v[142:143], v[132:133], v[132:133]
	v_add_f32_e32 v130, v130, v131
	v_pk_fma_f32 v[128:129], v[128:129], s[6:7], v[118:119] op_sel_hi:[1,0,0] neg_lo:[0,0,1] neg_hi:[0,0,1]
	v_add_f32_e32 v130, v142, v130
	v_pk_mul_f32 v[144:145], v[128:129], v[128:129]
	v_add_f32_e32 v130, v143, v130
	v_pk_fma_f32 v[118:119], v[114:115], s[6:7], v[118:119] op_sel_hi:[1,0,0] neg_lo:[0,0,1] neg_hi:[0,0,1]
	v_add_f32_e32 v130, v144, v130
	v_pk_mul_f32 v[114:115], v[118:119], v[118:119]
	v_add_f32_e32 v130, v145, v130
	v_add_f32_e32 v114, v114, v130
	v_add_f32_e32 v114, v115, v114
	s_mov_b64 s[6:7], 0x2000
	v_lshl_add_u64 v[188:189], v[188:189], 0, s[6:7]
	s_mov_b64 s[6:7], 0x7000
	v_lshl_add_u64 v[190:191], v[190:191], 0, s[6:7]
	s_waitcnt lgkmcnt(0)
	s_nop 1
	v_add_f32_dpp v114, v114, v114 quad_perm:[1,0,3,2] row_mask:0xf bank_mask:0xf
	s_waitcnt lgkmcnt(0)
	s_nop 1
	v_add_f32_dpp v114, v114, v114 quad_perm:[2,3,0,1] row_mask:0xf bank_mask:0xf
	s_waitcnt lgkmcnt(0)
	s_nop 1
	v_add_f32_dpp v114, v114, v114 row_half_mirror row_mask:0xf bank_mask:0xf
	v_fmamk_f32 v114, v114, 0x3c800000, v234
	v_cmp_gt_f32_e32 vcc, s85, v114
	v_mul_f32_e32 v115, 0x4b800000, v114
	s_nop 0
	v_cndmask_b32_e32 v114, v114, v115, vcc
	v_rsq_f32_e32 v114, v114
	s_nop 0
	v_mul_f32_e32 v115, 0x45800000, v114
	v_cndmask_b32_e32 v130, v114, v115, vcc
	v_pk_mul_f32 v[114:115], v[126:127], v[130:131] op_sel_hi:[1,0]
	v_pk_mul_f32 v[126:127], v[132:133], v[130:131] op_sel_hi:[1,0]
	v_pk_fma_f32 v[114:115], v[84:85], v[114:115], v[92:93]
	v_pk_fma_f32 v[126:127], v[86:87], v[126:127], v[94:95]
	v_pk_fma_f32 v[114:115], v[138:139], v[136:137], v[114:115] op_sel_hi:[1,0,1]
	v_pk_fma_f32 v[112:113], v[112:113], v[136:137], v[126:127] op_sel_hi:[1,0,1]
	v_pk_mul_f32 v[114:115], v[114:115], v[140:141]
	v_pk_mul_f32 v[112:113], v[112:113], v[116:117]
	v_cvt_pk_f16_f32 v114, v114, v115
	v_cvt_pk_f16_f32 v115, v112, v113
	v_pk_mul_f32 v[112:113], v[128:129], v[130:131] op_sel_hi:[1,0]
	s_nop 0
	v_pk_fma_f32 v[112:113], v[88:89], v[112:113], v[108:109]
	s_nop 0
	v_pk_fma_f32 v[112:113], v[120:121], v[136:137], v[112:113] op_sel_hi:[1,0,1]
	s_nop 0
	v_pk_mul_f32 v[112:113], v[112:113], v[124:125]
	s_nop 0
	v_cvt_pk_f16_f32 v116, v112, v113
	v_pk_mul_f32 v[112:113], v[118:119], v[130:131] op_sel_hi:[1,0]
	v_cvt_f32_f16_e32 v118, v135
	v_cvt_f32_f16_sdwa v119, v135 dst_sel:DWORD dst_unused:UNUSED_PAD src0_sel:WORD_1
	v_pk_fma_f32 v[112:113], v[90:91], v[112:113], v[110:111]
	s_nop 0
	v_pk_fma_f32 v[112:113], v[122:123], v[136:137], v[112:113] op_sel_hi:[1,0,1]
	s_nop 0
	v_pk_mul_f32 v[112:113], v[112:113], v[118:119]
	s_nop 0
	v_cvt_pk_f16_f32 v117, v112, v113
	global_store_dwordx4 v[192:193], v[114:117], off
	s_cbranch_scc0 .LBB0_123
